# M1 set-up: the six rel-bias table loads of a thread issued together (one round trip instead of three); on saddr K-loops
# speedup vs baseline: 1.0067x; 1.0067x over previous
.LBB0_359:
	s_mov_b32 s2, s72
	s_mov_b32 s4, s74
	s_waitcnt lgkmcnt(0)
	s_barrier
	v_mbcnt_lo_u32_b32 v7, -1, 0
	v_mbcnt_hi_u32_b32 v7, -1, v7
	s_movk_i32 s2, 0xc00
	v_add_u32_e32 v0, s76, v7
	s_mov_b64 s[22:23], s[0:1]
	v_cmp_gt_i32_e32 vcc, s2, v0
	s_and_saveexec_b64 s[20:21], vcc
	s_movk_i32 s6, 0x140
	s_movk_i32 s7, 0x180
	s_mov_b32 s8, 0x2aaaaaab
	s_cbranch_execz .LBB0_371
	s_load_dwordx2 s[4:5], s[22:23], 0x70
	s_mul_i32 s2, s18, 0x2800
	v_lshlrev_b32_e32 v4, 2, v0
	v_add_u32_e32 v4, 0x24000, v4
	s_waitcnt lgkmcnt(0)
	s_add_u32 s22, s4, s2
	s_addc_u32 s23, s5, 0
	v_add_u32_e32 v1, 0x0, v0
	v_mul_hi_i32 v2, v1, s8
	v_sub_u32_e32 v1, 0x17e, v1
	v_ashrrev_i32_e32 v2, 6, v2
	v_mad_i32_i24 v3, v2, s7, v1
	v_med3_i32 v3, v3, 0, v238
	v_mad_i32_i24 v3, v2, s6, v3
	v_lshlrev_b32_e32 v3, 2, v3
	global_load_dword v5, v3, s[22:23]
	v_add_u32_e32 v1, 0x200, v0
	v_mul_hi_i32 v2, v1, s8
	v_sub_u32_e32 v1, 0x17e, v1
	v_ashrrev_i32_e32 v2, 6, v2
	v_mad_i32_i24 v3, v2, s7, v1
	v_med3_i32 v3, v3, 0, v238
	v_mad_i32_i24 v3, v2, s6, v3
	v_lshlrev_b32_e32 v3, 2, v3
	global_load_dword v6, v3, s[22:23]
	v_add_u32_e32 v1, 0x400, v0
	v_mul_hi_i32 v2, v1, s8
	v_sub_u32_e32 v1, 0x17e, v1
	v_ashrrev_i32_e32 v2, 6, v2
	v_mad_i32_i24 v3, v2, s7, v1
	v_med3_i32 v3, v3, 0, v238
	v_mad_i32_i24 v3, v2, s6, v3
	v_lshlrev_b32_e32 v3, 2, v3
	global_load_dword v7, v3, s[22:23]
	v_add_u32_e32 v1, 0x600, v0
	v_mul_hi_i32 v2, v1, s8
	v_sub_u32_e32 v1, 0x17e, v1
	v_ashrrev_i32_e32 v2, 6, v2
	v_mad_i32_i24 v3, v2, s7, v1
	v_med3_i32 v3, v3, 0, v238
	v_mad_i32_i24 v3, v2, s6, v3
	v_lshlrev_b32_e32 v3, 2, v3
	global_load_dword v8, v3, s[22:23]
	v_add_u32_e32 v1, 0x800, v0
	v_mul_hi_i32 v2, v1, s8
	v_sub_u32_e32 v1, 0x17e, v1
	v_ashrrev_i32_e32 v2, 6, v2
	v_mad_i32_i24 v3, v2, s7, v1
	v_med3_i32 v3, v3, 0, v238
	v_mad_i32_i24 v3, v2, s6, v3
	v_lshlrev_b32_e32 v3, 2, v3
	global_load_dword v9, v3, s[22:23]
	v_add_u32_e32 v1, 0xa00, v0
	v_mul_hi_i32 v2, v1, s8
	v_sub_u32_e32 v1, 0x17e, v1
	v_ashrrev_i32_e32 v2, 6, v2
	v_mad_i32_i24 v3, v2, s7, v1
	v_med3_i32 v3, v3, 0, v238
	v_mad_i32_i24 v3, v2, s6, v3
	v_lshlrev_b32_e32 v3, 2, v3
	global_load_dword v10, v3, s[22:23]
	s_waitcnt vmcnt(5)
	v_mul_f32_e32 v5, 0x3fb8aa3b, v5
	ds_write_b32 v4, v5
	s_waitcnt vmcnt(4)
	v_mul_f32_e32 v6, 0x3fb8aa3b, v6
	ds_write_b32 v4, v6 offset:2048
	s_waitcnt vmcnt(3)
	v_mul_f32_e32 v7, 0x3fb8aa3b, v7
	ds_write_b32 v4, v7 offset:4096
	s_waitcnt vmcnt(2)
	v_mul_f32_e32 v8, 0x3fb8aa3b, v8
	ds_write_b32 v4, v8 offset:6144
	s_waitcnt vmcnt(1)
	v_mul_f32_e32 v9, 0x3fb8aa3b, v9
	ds_write_b32 v4, v9 offset:8192
	s_waitcnt vmcnt(0)
	v_mul_f32_e32 v10, 0x3fb8aa3b, v10
	ds_write_b32 v4, v10 offset:10240
